# attention window mask via v_cmp+v_cndmask on prev/next scalar paths (no per-element index arithmetic)
# speedup vs baseline: 1.0227x; 1.0031x over previous
; #define LAS __attribute__((address_space(3)))
; __device__ __forceinline__ void attn_unit(const bf16* proj, unsigned char* ws, LAS unsigned char* lds, int a) {
;     ...
;         f32x4 st[2][8];
; #pragma unroll
;         for (int kt = 0; kt < 8; ++kt) { st[0][kt] = (f32x4){0.f, 0.f, 0.f, 0.f}; st[1][kt] = (f32x4){0.f, 0.f, 0.f, 0.f}; }
; #pragma unroll
;         for (int s = 0; s < 4; ++s) {
;             const bf16x8 qa = *(const LAS bf16x8*)(qbase + 64 * s), qb = *(const LAS bf16x8*)(qbase + 16 * QK_STRIDE + 64 * s);
; #pragma unroll
;             for (int kt = 0; kt < 8; ++kt) {
;                 const bf16x8 kf = *(const LAS bf16x8*)(KS + (16 * kt + fr) * QK_STRIDE + (32 * s + 8 * fq) * 2);
;                 st[0][kt] = __builtin_amdgcn_mfma_f32_16x16x32_bf16(kf, qa, st[0][kt], 0, 0, 0);
;                 st[1][kt] = __builtin_amdgcn_mfma_f32_16x16x32_bf16(kf, qb, st[1][kt], 0, 0, 0);
;             }
;         }
.LBB0_608:
	ds_read_b128 v[92:95], v205
	ds_read_b128 v[100:103], v205 offset:4352
	ds_read_b128 v[104:107], v201
	ds_read_b128 v[112:115], v201 offset:4352
	ds_read_b128 v[120:123], v201 offset:8704
	ds_read_b128 v[128:131], v201 offset:13056
	ds_read_b128 v[136:139], v201 offset:17408
	ds_read_b128 v[144:147], v201 offset:21760
	ds_read_b128 v[152:155], v201 offset:26112
	ds_read_b128 v[210:213], v201 offset:30464
	s_waitcnt lgkmcnt(7)
	v_mfma_f32_16x16x32_bf16 v[108:111], v[104:107], v[92:95], 0
	s_cmp_lg_u32 s72, s51
	s_cselect_b64 s[56:57], -1, 0
	s_cmp_lt_u32 s70, s69
	v_mfma_f32_16x16x32_bf16 v[104:107], v[104:107], v[100:103], 0
	s_cselect_b64 s[4:5], -1, 0
	v_sub_u32_e32 v207, 0, v181
	v_cndmask_b32_e64 v207, v207, v181, s[4:5]
	s_waitcnt lgkmcnt(6)
	v_mfma_f32_16x16x32_bf16 v[116:119], v[112:115], v[92:95], 0
	s_cmp_eq_u32 s72, s51
	v_mfma_f32_16x16x32_bf16 v[112:115], v[112:115], v[100:103], 0
	s_waitcnt lgkmcnt(5)
	v_mfma_f32_16x16x32_bf16 v[124:127], v[120:123], v[92:95], 0
	v_mfma_f32_16x16x32_bf16 v[120:123], v[120:123], v[100:103], 0
	s_waitcnt lgkmcnt(4)
	v_mfma_f32_16x16x32_bf16 v[132:135], v[128:131], v[92:95], 0
	v_mfma_f32_16x16x32_bf16 v[128:131], v[128:131], v[100:103], 0
	s_waitcnt lgkmcnt(3)
	v_mfma_f32_16x16x32_bf16 v[140:143], v[136:139], v[92:95], 0
	v_mfma_f32_16x16x32_bf16 v[136:139], v[136:139], v[100:103], 0
	s_waitcnt lgkmcnt(2)
	v_mfma_f32_16x16x32_bf16 v[148:151], v[144:147], v[92:95], 0
	v_mfma_f32_16x16x32_bf16 v[144:147], v[144:147], v[100:103], 0
	s_waitcnt lgkmcnt(1)
	v_mfma_f32_16x16x32_bf16 v[156:159], v[152:155], v[92:95], 0
	v_mfma_f32_16x16x32_bf16 v[152:155], v[152:155], v[100:103], 0
	s_waitcnt lgkmcnt(0)
	v_mfma_f32_16x16x32_bf16 v[92:95], v[210:213], v[92:95], 0
	v_mfma_f32_16x16x32_bf16 v[100:103], v[210:213], v[100:103], 0
	ds_read_b128 v[210:213], v205 offset:64
	ds_read_b128 v[214:217], v205 offset:4416
	ds_read_b128 v[218:221], v201 offset:64
	s_waitcnt lgkmcnt(0)
	v_mfma_f32_16x16x32_bf16 v[108:111], v[218:221], v[210:213], v[108:111]
	v_mfma_f32_16x16x32_bf16 v[104:107], v[218:221], v[214:217], v[104:107]
	ds_read_b128 v[218:221], v201 offset:4416
	s_waitcnt lgkmcnt(0)
	v_mfma_f32_16x16x32_bf16 v[116:119], v[218:221], v[210:213], v[116:119]
	v_mfma_f32_16x16x32_bf16 v[112:115], v[218:221], v[214:217], v[112:115]
	ds_read_b128 v[218:221], v201 offset:8768
	s_waitcnt lgkmcnt(0)
	v_mfma_f32_16x16x32_bf16 v[124:127], v[218:221], v[210:213], v[124:127]
	v_mfma_f32_16x16x32_bf16 v[120:123], v[218:221], v[214:217], v[120:123]
	ds_read_b128 v[218:221], v201 offset:13120
	s_waitcnt lgkmcnt(0)
	v_mfma_f32_16x16x32_bf16 v[132:135], v[218:221], v[210:213], v[132:135]
	v_mfma_f32_16x16x32_bf16 v[128:131], v[218:221], v[214:217], v[128:131]
	ds_read_b128 v[218:221], v201 offset:17472
	s_waitcnt lgkmcnt(0)
	v_mfma_f32_16x16x32_bf16 v[140:143], v[218:221], v[210:213], v[140:143]
	v_mfma_f32_16x16x32_bf16 v[136:139], v[218:221], v[214:217], v[136:139]
	ds_read_b128 v[218:221], v201 offset:21824
	s_waitcnt lgkmcnt(0)
	v_mfma_f32_16x16x32_bf16 v[148:151], v[218:221], v[210:213], v[148:151]
	v_mfma_f32_16x16x32_bf16 v[144:147], v[218:221], v[214:217], v[144:147]
	ds_read_b128 v[218:221], v201 offset:26176
	s_waitcnt lgkmcnt(0)
	v_mfma_f32_16x16x32_bf16 v[156:159], v[218:221], v[210:213], v[156:159]
	v_mfma_f32_16x16x32_bf16 v[152:155], v[218:221], v[214:217], v[152:155]
	ds_read_b128 v[218:221], v201 offset:30528
	s_waitcnt lgkmcnt(0)
	v_mfma_f32_16x16x32_bf16 v[92:95], v[218:221], v[210:213], v[92:95]
	v_mfma_f32_16x16x32_bf16 v[100:103], v[218:221], v[214:217], v[100:103]
	ds_read_b128 v[210:213], v205 offset:128
	ds_read_b128 v[214:217], v205 offset:4480
	ds_read_b128 v[218:221], v201 offset:128
	s_waitcnt lgkmcnt(0)
	v_mfma_f32_16x16x32_bf16 v[108:111], v[218:221], v[210:213], v[108:111]
	v_mfma_f32_16x16x32_bf16 v[104:107], v[218:221], v[214:217], v[104:107]
	ds_read_b128 v[218:221], v201 offset:4480
	s_waitcnt lgkmcnt(0)
	v_mfma_f32_16x16x32_bf16 v[116:119], v[218:221], v[210:213], v[116:119]
	v_mfma_f32_16x16x32_bf16 v[112:115], v[218:221], v[214:217], v[112:115]
	ds_read_b128 v[218:221], v201 offset:8832
	s_waitcnt lgkmcnt(0)
	v_mfma_f32_16x16x32_bf16 v[124:127], v[218:221], v[210:213], v[124:127]
	v_mfma_f32_16x16x32_bf16 v[120:123], v[218:221], v[214:217], v[120:123]
	ds_read_b128 v[218:221], v201 offset:13184
	s_waitcnt lgkmcnt(0)
	v_mfma_f32_16x16x32_bf16 v[222:225], v[218:221], v[210:213], v[132:135]
	s_nop 2
	ds_read_b128 v[132:135], v201 offset:17536
	v_mfma_f32_16x16x32_bf16 v[128:131], v[218:221], v[214:217], v[128:131]
	s_waitcnt lgkmcnt(0)
	v_mfma_f32_16x16x32_bf16 v[218:221], v[132:135], v[210:213], v[140:143]
	v_mfma_f32_16x16x32_bf16 v[226:229], v[132:135], v[214:217], v[136:139]
	ds_read_b128 v[132:135], v201 offset:21888
	s_waitcnt lgkmcnt(0)
	v_mfma_f32_16x16x32_bf16 v[148:151], v[132:135], v[210:213], v[148:151]
	v_mfma_f32_16x16x32_bf16 v[230:233], v[132:135], v[214:217], v[144:147]
	ds_read_b128 v[132:135], v201 offset:26240
	s_waitcnt lgkmcnt(0)
	v_mfma_f32_16x16x32_bf16 v[156:159], v[132:135], v[210:213], v[156:159]
	v_mfma_f32_16x16x32_bf16 v[234:237], v[132:135], v[214:217], v[152:155]
	ds_read_b128 v[132:135], v201 offset:30592
	s_waitcnt lgkmcnt(0)
	v_mfma_f32_16x16x32_bf16 v[214:217], v[132:135], v[214:217], v[100:103]
	ds_read_b128 v[238:241], v205 offset:192
	ds_read_b128 v[242:245], v205 offset:4544
	s_nop 0
	ds_read_b128 v[100:103], v201 offset:192
	s_waitcnt lgkmcnt(0)
	v_mfma_f32_16x16x32_bf16 v[140:143], v[100:103], v[242:245], v[104:107]
	s_nop 2
	ds_read_b128 v[104:107], v201 offset:4544
	v_mfma_f32_16x16x32_bf16 v[210:213], v[132:135], v[210:213], v[92:95]
	v_mfma_f32_16x16x32_bf16 v[92:95], v[100:103], v[238:241], v[108:111]
	s_nop 2
	ds_read_b128 v[108:111], v201 offset:8896
	s_waitcnt lgkmcnt(1)
; #define LAS __attribute__((address_space(3)))
; __device__ __forceinline__ void attn_unit(const bf16* proj, unsigned char* ws, LAS unsigned char* lds, int a) {
;     ...
;         for (int s = 0; s < 4; ++s) {
;             const bf16x8 qa = *(const LAS bf16x8*)(qbase + 64 * s), qb = *(const LAS bf16x8*)(qbase + 16 * QK_STRIDE + 64 * s);
; #pragma unroll
;             for (int kt = 0; kt < 8; ++kt) {
;                 const bf16x8 kf = *(const LAS bf16x8*)(KS + (16 * kt + fr) * QK_STRIDE + (32 * s + 8 * fq) * 2);
;                 st[0][kt] = __builtin_amdgcn_mfma_f32_16x16x32_bf16(kf, qa, st[0][kt], 0, 0, 0);
;                 st[1][kt] = __builtin_amdgcn_mfma_f32_16x16x32_bf16(kf, qb, st[1][kt], 0, 0, 0);
;             }
;         }
;         bf16x8 pb[2][4];
; #pragma unroll
;         for (int rt = 0; rt < 2; ++rt) {
;             const int qi = rq * 32 + rt * 16 + fr;
;             if (kb != n) {
;                 const int sgn = (kb < n) ? 1 : -1, dbase = sgn * (4 * fq - qi);
; #pragma unroll
;                 for (int kt = 0; kt < 8; ++kt)
; #pragma unroll
;                     for (int r = 0; r < 4; ++r) { const int dd = dbase + sgn * (16 * kt + r); st[rt][kt][r] += __builtin_bit_cast(float, (unsigned)(dd >> 31) & 0xF149F2CAu); }
;             }
	v_mfma_f32_16x16x32_bf16 v[136:139], v[104:107], v[242:245], v[112:115]
	s_nop 2
	ds_read_b128 v[112:115], v201 offset:13248
	v_mfma_f32_16x16x32_bf16 v[100:103], v[104:107], v[238:241], v[116:119]
	s_waitcnt lgkmcnt(1)
	v_mfma_f32_16x16x32_bf16 v[104:107], v[108:111], v[238:241], v[124:127]
	v_mfma_f32_16x16x32_bf16 v[132:135], v[108:111], v[242:245], v[120:123]
	s_waitcnt lgkmcnt(0)
	v_mfma_f32_16x16x32_bf16 v[108:111], v[112:115], v[238:241], v[222:225]
	v_mfma_f32_16x16x32_bf16 v[128:131], v[112:115], v[242:245], v[128:131]
	ds_read_b128 v[112:115], v201 offset:17600
	s_waitcnt lgkmcnt(0)
	v_mfma_f32_16x16x32_bf16 v[144:147], v[112:115], v[238:241], v[218:221]
	v_mfma_f32_16x16x32_bf16 v[124:127], v[112:115], v[242:245], v[226:229]
	ds_read_b128 v[112:115], v201 offset:21952
	s_waitcnt lgkmcnt(0)
	v_mfma_f32_16x16x32_bf16 v[148:151], v[112:115], v[238:241], v[148:151]
	v_mfma_f32_16x16x32_bf16 v[120:123], v[112:115], v[242:245], v[230:233]
	ds_read_b128 v[112:115], v201 offset:26304
	s_waitcnt lgkmcnt(0)
	v_mfma_f32_16x16x32_bf16 v[152:155], v[112:115], v[238:241], v[156:159]
	v_mfma_f32_16x16x32_bf16 v[116:119], v[112:115], v[242:245], v[234:237]
	ds_read_b128 v[112:115], v201 offset:30656
	s_waitcnt lgkmcnt(0)
	v_mfma_f32_16x16x32_bf16 v[156:159], v[112:115], v[238:241], v[210:213]
	s_nop 2
	v_mfma_f32_16x16x32_bf16 v[112:115], v[112:115], v[242:245], v[214:217]
	s_nop 3
	s_cbranch_scc1 .LBB0_610
	s_cmp_lt_u32 s70, s69
	s_cbranch_scc0 .Lam_a_next
	v_cmp_gt_i32_e32 vcc, 0, v181
	v_cndmask_b32_e32 v92, v92, v171, vcc
	v_cmp_gt_i32_e32 vcc, -1, v181
	v_cndmask_b32_e32 v93, v93, v171, vcc
	v_cmp_gt_i32_e32 vcc, -2, v181
	v_cndmask_b32_e32 v94, v94, v171, vcc
	v_cmp_gt_i32_e32 vcc, -3, v181
	v_cndmask_b32_e32 v95, v95, v171, vcc
	v_cmp_gt_i32_e32 vcc, -16, v181
	v_cndmask_b32_e32 v100, v100, v171, vcc
	v_cmp_gt_i32_e32 vcc, 0xffffffef, v181
	v_cndmask_b32_e32 v101, v101, v171, vcc
	v_cmp_gt_i32_e32 vcc, 0xffffffee, v181
	v_cndmask_b32_e32 v102, v102, v171, vcc
	v_cmp_gt_i32_e32 vcc, 0xffffffed, v181
	v_cndmask_b32_e32 v103, v103, v171, vcc
	v_cmp_gt_i32_e32 vcc, 0xffffffe0, v181
	v_cndmask_b32_e32 v104, v104, v171, vcc
	v_cmp_gt_i32_e32 vcc, 0xffffffdf, v181
	v_cndmask_b32_e32 v105, v105, v171, vcc
	v_cmp_gt_i32_e32 vcc, 0xffffffde, v181
	v_cndmask_b32_e32 v106, v106, v171, vcc
	v_cmp_gt_i32_e32 vcc, 0xffffffdd, v181
	v_cndmask_b32_e32 v107, v107, v171, vcc
	v_cmp_gt_i32_e32 vcc, 0xffffffd0, v181
	v_cndmask_b32_e32 v108, v108, v171, vcc
	v_cmp_gt_i32_e32 vcc, 0xffffffcf, v181
	v_cndmask_b32_e32 v109, v109, v171, vcc
	v_cmp_gt_i32_e32 vcc, 0xffffffce, v181
	v_cndmask_b32_e32 v110, v110, v171, vcc
	v_cmp_gt_i32_e32 vcc, 0xffffffcd, v181
	v_cndmask_b32_e32 v111, v111, v171, vcc
	v_cmp_gt_i32_e32 vcc, 0xffffffc0, v181
	v_cndmask_b32_e32 v144, v144, v171, vcc
	v_cmp_gt_i32_e32 vcc, 0xffffffbf, v181
	v_cndmask_b32_e32 v145, v145, v171, vcc
	v_cmp_gt_i32_e32 vcc, 0xffffffbe, v181
	v_cndmask_b32_e32 v146, v146, v171, vcc
	v_cmp_gt_i32_e32 vcc, 0xffffffbd, v181
	v_cndmask_b32_e32 v147, v147, v171, vcc
	v_cmp_gt_i32_e32 vcc, 0xffffffb0, v181
	v_cndmask_b32_e32 v148, v148, v171, vcc
	v_cmp_gt_i32_e32 vcc, 0xffffffaf, v181
	v_cndmask_b32_e32 v149, v149, v171, vcc
	v_cmp_gt_i32_e32 vcc, 0xffffffae, v181
	v_cndmask_b32_e32 v150, v150, v171, vcc
	v_cmp_gt_i32_e32 vcc, 0xffffffad, v181
	v_cndmask_b32_e32 v151, v151, v171, vcc
	v_cmp_gt_i32_e32 vcc, 0xffffffa0, v181
	v_cndmask_b32_e32 v152, v152, v171, vcc
	v_cmp_gt_i32_e32 vcc, 0xffffff9f, v181
	v_cndmask_b32_e32 v153, v153, v171, vcc
	v_cmp_gt_i32_e32 vcc, 0xffffff9e, v181
	v_cndmask_b32_e32 v154, v154, v171, vcc
	v_cmp_gt_i32_e32 vcc, 0xffffff9d, v181
	v_cndmask_b32_e32 v155, v155, v171, vcc
	v_cmp_gt_i32_e32 vcc, 0xffffff90, v181
	v_cndmask_b32_e32 v156, v156, v171, vcc
	v_cmp_gt_i32_e32 vcc, 0xffffff8f, v181
	v_cndmask_b32_e32 v157, v157, v171, vcc
	v_cmp_gt_i32_e32 vcc, 0xffffff8e, v181
	v_cndmask_b32_e32 v158, v158, v171, vcc
	v_cmp_gt_i32_e32 vcc, 0xffffff8d, v181
	v_cndmask_b32_e32 v159, v159, v171, vcc
	s_branch .LBB0_610
.Lam_a_next:
	v_cmp_lt_i32_e32 vcc, 0, v181
	v_cndmask_b32_e32 v92, v92, v171, vcc
	v_cmp_lt_i32_e32 vcc, -1, v181
	v_cndmask_b32_e32 v93, v93, v171, vcc
	v_cmp_lt_i32_e32 vcc, -2, v181
	v_cndmask_b32_e32 v94, v94, v171, vcc
	v_cmp_lt_i32_e32 vcc, -3, v181
	v_cndmask_b32_e32 v95, v95, v171, vcc
	v_cmp_lt_i32_e32 vcc, -16, v181
	v_cndmask_b32_e32 v100, v100, v171, vcc
	v_cmp_lt_i32_e32 vcc, 0xffffffef, v181
	v_cndmask_b32_e32 v101, v101, v171, vcc
	v_cmp_lt_i32_e32 vcc, 0xffffffee, v181
	v_cndmask_b32_e32 v102, v102, v171, vcc
	v_cmp_lt_i32_e32 vcc, 0xffffffed, v181
	v_cndmask_b32_e32 v103, v103, v171, vcc
	v_cmp_lt_i32_e32 vcc, 0xffffffe0, v181
	v_cndmask_b32_e32 v104, v104, v171, vcc
	v_cmp_lt_i32_e32 vcc, 0xffffffdf, v181
	v_cndmask_b32_e32 v105, v105, v171, vcc
	v_cmp_lt_i32_e32 vcc, 0xffffffde, v181
	v_cndmask_b32_e32 v106, v106, v171, vcc
	v_cmp_lt_i32_e32 vcc, 0xffffffdd, v181
	v_cndmask_b32_e32 v107, v107, v171, vcc
	v_cmp_lt_i32_e32 vcc, 0xffffffd0, v181
	v_cndmask_b32_e32 v108, v108, v171, vcc
	v_cmp_lt_i32_e32 vcc, 0xffffffcf, v181
	v_cndmask_b32_e32 v109, v109, v171, vcc
	v_cmp_lt_i32_e32 vcc, 0xffffffce, v181
	v_cndmask_b32_e32 v110, v110, v171, vcc
	v_cmp_lt_i32_e32 vcc, 0xffffffcd, v181
	v_cndmask_b32_e32 v111, v111, v171, vcc
	v_cmp_lt_i32_e32 vcc, 0xffffffc0, v181
	v_cndmask_b32_e32 v144, v144, v171, vcc
	v_cmp_lt_i32_e32 vcc, 0xffffffbf, v181
	v_cndmask_b32_e32 v145, v145, v171, vcc
	v_cmp_lt_i32_e32 vcc, 0xffffffbe, v181
	v_cndmask_b32_e32 v146, v146, v171, vcc
	v_cmp_lt_i32_e32 vcc, 0xffffffbd, v181
	v_cndmask_b32_e32 v147, v147, v171, vcc
	v_cmp_lt_i32_e32 vcc, 0xffffffb0, v181
	v_cndmask_b32_e32 v148, v148, v171, vcc
	v_cmp_lt_i32_e32 vcc, 0xffffffaf, v181
	v_cndmask_b32_e32 v149, v149, v171, vcc
	v_cmp_lt_i32_e32 vcc, 0xffffffae, v181
	v_cndmask_b32_e32 v150, v150, v171, vcc
	v_cmp_lt_i32_e32 vcc, 0xffffffad, v181
	v_cndmask_b32_e32 v151, v151, v171, vcc
	v_cmp_lt_i32_e32 vcc, 0xffffffa0, v181
	v_cndmask_b32_e32 v152, v152, v171, vcc
	v_cmp_lt_i32_e32 vcc, 0xffffff9f, v181
	v_cndmask_b32_e32 v153, v153, v171, vcc
	v_cmp_lt_i32_e32 vcc, 0xffffff9e, v181
	v_cndmask_b32_e32 v154, v154, v171, vcc
	v_cmp_lt_i32_e32 vcc, 0xffffff9d, v181
	v_cndmask_b32_e32 v155, v155, v171, vcc
	v_cmp_lt_i32_e32 vcc, 0xffffff90, v181
	v_cndmask_b32_e32 v156, v156, v171, vcc
	v_cmp_lt_i32_e32 vcc, 0xffffff8f, v181
	v_cndmask_b32_e32 v157, v157, v171, vcc
	v_cmp_lt_i32_e32 vcc, 0xffffff8e, v181
	v_cndmask_b32_e32 v158, v158, v171, vcc
	v_cmp_lt_i32_e32 vcc, 0xffffff8d, v181
	v_cndmask_b32_e32 v159, v159, v171, vcc
; __device__ __forceinline__ unsigned pk2(float lo, float hi) { return pg8::cvt_pk_bf16(lo, hi); }
; __device__ __forceinline__ void attn_unit(const bf16* proj, unsigned char* ws, LAS unsigned char* lds, int a) {
;     ...
;             if (kb != n) {
;                 const int sgn = (kb < n) ? 1 : -1, dbase = sgn * (4 * fq - qi);
; #pragma unroll
;                 for (int kt = 0; kt < 8; ++kt)
; #pragma unroll
;                     for (int r = 0; r < 4; ++r) { const int dd = dbase + sgn * (16 * kt + r); st[rt][kt][r] += __builtin_bit_cast(float, (unsigned)(dd >> 31) & 0xF149F2CAu); }
;             }
;             float mx = -1e30f;
; #pragma unroll
;             for (int kt = 0; kt < 8; ++kt)
; #pragma unroll
;                 for (int r = 0; r < 4; ++r) mx = fmaxf(mx, st[rt][kt][r]);
;             mx = fmaxf(mx, __shfl_xor(mx, 16)); mx = fmaxf(mx, __shfl_xor(mx, 32));
;             const float mnew = fmaxf(mrow[rt], mx), alpha = __builtin_amdgcn_exp2f(mrow[rt] - mnew);
;             mrow[rt] = mnew; float ls = lrow[rt] * alpha;
; #pragma unroll
;             for (int dt = 0; dt < 8; ++dt) O[rt][dt] *= alpha;
; #pragma unroll
;             for (int kt = 0; kt < 8; ++kt)
; #pragma unroll
;                 for (int r = 0; r < 4; ++r) { const float p = __builtin_amdgcn_exp2f(st[rt][kt][r] - mnew); st[rt][kt][r] = p; ls += p; }
;             lrow[rt] = ls;
; #pragma unroll
;             for (int tp = 0; tp < 4; ++tp) {
;                 v4u w; w.x = pk2(st[rt][2 * tp][0], st[rt][2 * tp][1]); w.y = pk2(st[rt][2 * tp][2], st[rt][2 * tp][3]);
;                 w.z = pk2(st[rt][2 * tp + 1][0], st[rt][2 * tp + 1][1]); w.w = pk2(st[rt][2 * tp + 1][2], st[rt][2 * tp + 1][3]);
;                 pb[rt][tp] = __builtin_bit_cast(bf16x8, w);
;             }
.LBB0_610:
	v_max3_f32 v207, v92, s67, v93
	v_max3_f32 v207, v207, v94, v95
	v_max3_f32 v207, v207, v100, v101
	v_max3_f32 v207, v207, v102, v103
	v_max3_f32 v207, v207, v104, v105
	v_max3_f32 v207, v207, v106, v107
	v_max3_f32 v207, v207, v108, v109
	v_max3_f32 v207, v207, v110, v111
	v_max3_f32 v207, v207, v144, v145
	v_max3_f32 v207, v207, v146, v147
	v_max3_f32 v207, v207, v148, v149
	v_max3_f32 v207, v207, v150, v151
	v_max3_f32 v207, v207, v152, v153
	v_max3_f32 v207, v207, v154, v155
	v_max3_f32 v207, v207, v156, v157
	v_max3_f32 v207, v207, v158, v159
	ds_bpermute_b32 v238, v203, v207
	s_andn2_b64 vcc, exec, s[56:57]
	s_waitcnt lgkmcnt(0)
	v_max_f32_e32 v238, v238, v238
	v_max_f32_e32 v207, v207, v238
	ds_bpermute_b32 v238, v204, v207
	s_waitcnt lgkmcnt(0)
	v_max3_f32 v207, v209, v207, v238
	v_sub_f32_e32 v92, v92, v207
	v_exp_f32_e32 v238, v92
	v_sub_f32_e32 v92, v101, v207
	v_exp_f32_e32 v243, v92
	v_sub_f32_e32 v92, v102, v207
	v_exp_f32_e32 v244, v92
	v_sub_f32_e32 v92, v103, v207
	v_exp_f32_e32 v245, v92
	v_sub_f32_e32 v92, v104, v207
	v_exp_f32_e32 v246, v92
	v_sub_f32_e32 v92, v105, v207
	v_exp_f32_e32 v247, v92
	v_sub_f32_e32 v92, v106, v207
	v_exp_f32_e32 v248, v92
	v_sub_f32_e32 v92, v107, v207
	v_exp_f32_e32 v249, v92
	v_sub_f32_e32 v92, v108, v207
	v_exp_f32_e32 v250, v92
	v_sub_f32_e32 v92, v109, v207
	v_exp_f32_e32 v251, v92
	v_sub_f32_e32 v92, v110, v207
	v_exp_f32_e32 v252, v92
	v_sub_f32_e32 v92, v111, v207
	v_exp_f32_e32 v253, v92
	v_sub_f32_e32 v92, v144, v207
	v_exp_f32_e32 v144, v92
	v_sub_f32_e32 v92, v145, v207
	v_exp_f32_e32 v145, v92
	v_sub_f32_e32 v92, v146, v207
	v_exp_f32_e32 v146, v92
	v_sub_f32_e32 v92, v147, v207
	v_exp_f32_e32 v147, v92
	v_sub_f32_e32 v92, v148, v207
	v_exp_f32_e32 v148, v92
	v_sub_f32_e32 v92, v149, v207
	v_exp_f32_e32 v149, v92
	v_sub_f32_e32 v92, v150, v207
	v_exp_f32_e32 v150, v92
	v_sub_f32_e32 v92, v151, v207
	v_exp_f32_e32 v151, v92
	v_sub_f32_e32 v92, v152, v207
	v_exp_f32_e32 v152, v92
	v_sub_f32_e32 v92, v153, v207
	v_exp_f32_e32 v153, v92
	v_sub_f32_e32 v92, v154, v207
	v_exp_f32_e32 v154, v92
	v_sub_f32_e32 v92, v155, v207
	v_exp_f32_e32 v155, v92
	v_sub_f32_e32 v92, v156, v207
	v_exp_f32_e32 v156, v92
	v_sub_f32_e32 v92, v157, v207
	v_exp_f32_e32 v157, v92
	v_sub_f32_e32 v92, v158, v207
	v_sub_f32_e32 v93, v93, v207
	v_sub_f32_e32 v94, v94, v207
	v_sub_f32_e32 v95, v95, v207
	v_sub_f32_e32 v100, v100, v207
	v_exp_f32_e32 v158, v92
	v_sub_f32_e32 v92, v159, v207
	v_exp_f32_e32 v239, v93
	v_exp_f32_e32 v240, v94
	v_exp_f32_e32 v241, v95
	v_exp_f32_e32 v242, v100
	v_exp_f32_e32 v159, v92
	v_cvt_pk_bf16_f32 v108, v238, v239
	v_cvt_pk_bf16_f32 v109, v240, v241
	v_cvt_pk_bf16_f32 v110, v242, v243
	v_cvt_pk_bf16_f32 v111, v244, v245
	v_cvt_pk_bf16_f32 v104, v246, v247
	v_cvt_pk_bf16_f32 v105, v248, v249
	v_cvt_pk_bf16_f32 v106, v250, v251
	v_cvt_pk_bf16_f32 v107, v252, v253
	v_cvt_pk_bf16_f32 v100, v144, v145
	v_cvt_pk_bf16_f32 v101, v146, v147
	v_cvt_pk_bf16_f32 v102, v148, v149
	v_cvt_pk_bf16_f32 v103, v150, v151
	v_cvt_pk_bf16_f32 v92, v152, v153
	v_cvt_pk_bf16_f32 v93, v154, v155
	v_cvt_pk_bf16_f32 v94, v156, v157
	v_cvt_pk_bf16_f32 v95, v158, v159
	s_cbranch_vccnz .LBB0_612
	s_cmp_lt_u32 s70, s69
	s_cbranch_scc0 .Lam_b_next
	v_cmp_gt_i32_e32 vcc, 0, v181
	v_cndmask_b32_e32 v136, v136, v171, vcc
	v_cmp_gt_i32_e32 vcc, -1, v181
	v_cndmask_b32_e32 v137, v137, v171, vcc
	v_cmp_gt_i32_e32 vcc, -2, v181
	v_cndmask_b32_e32 v138, v138, v171, vcc
	v_cmp_gt_i32_e32 vcc, -3, v181
	v_cndmask_b32_e32 v139, v139, v171, vcc
	v_cmp_gt_i32_e32 vcc, -16, v181
	v_cndmask_b32_e32 v132, v132, v171, vcc
	v_cmp_gt_i32_e32 vcc, 0xffffffef, v181
	v_cndmask_b32_e32 v133, v133, v171, vcc
	v_cmp_gt_i32_e32 vcc, 0xffffffee, v181
	v_cndmask_b32_e32 v134, v134, v171, vcc
	v_cmp_gt_i32_e32 vcc, 0xffffffed, v181
	v_cndmask_b32_e32 v135, v135, v171, vcc
	v_cmp_gt_i32_e32 vcc, 0xffffffe0, v181
	v_cndmask_b32_e32 v128, v128, v171, vcc
	v_cmp_gt_i32_e32 vcc, 0xffffffdf, v181
	v_cndmask_b32_e32 v129, v129, v171, vcc
	v_cmp_gt_i32_e32 vcc, 0xffffffde, v181
	v_cndmask_b32_e32 v130, v130, v171, vcc
	v_cmp_gt_i32_e32 vcc, 0xffffffdd, v181
	v_cndmask_b32_e32 v131, v131, v171, vcc
	v_cmp_gt_i32_e32 vcc, 0xffffffd0, v181
	v_cndmask_b32_e32 v124, v124, v171, vcc
	v_cmp_gt_i32_e32 vcc, 0xffffffcf, v181
	v_cndmask_b32_e32 v125, v125, v171, vcc
	v_cmp_gt_i32_e32 vcc, 0xffffffce, v181
	v_cndmask_b32_e32 v126, v126, v171, vcc
	v_cmp_gt_i32_e32 vcc, 0xffffffcd, v181
	v_cndmask_b32_e32 v127, v127, v171, vcc
	v_cmp_gt_i32_e32 vcc, 0xffffffc0, v181
	v_cndmask_b32_e32 v120, v120, v171, vcc
	v_cmp_gt_i32_e32 vcc, 0xffffffbf, v181
	v_cndmask_b32_e32 v121, v121, v171, vcc
	v_cmp_gt_i32_e32 vcc, 0xffffffbe, v181
	v_cndmask_b32_e32 v122, v122, v171, vcc
	v_cmp_gt_i32_e32 vcc, 0xffffffbd, v181
	v_cndmask_b32_e32 v123, v123, v171, vcc
	v_cmp_gt_i32_e32 vcc, 0xffffffb0, v181
	v_cndmask_b32_e32 v116, v116, v171, vcc
	v_cmp_gt_i32_e32 vcc, 0xffffffaf, v181
	v_cndmask_b32_e32 v117, v117, v171, vcc
	v_cmp_gt_i32_e32 vcc, 0xffffffae, v181
	v_cndmask_b32_e32 v118, v118, v171, vcc
	v_cmp_gt_i32_e32 vcc, 0xffffffad, v181
	v_cndmask_b32_e32 v119, v119, v171, vcc
	v_cmp_gt_i32_e32 vcc, 0xffffffa0, v181
	v_cndmask_b32_e32 v112, v112, v171, vcc
	v_cmp_gt_i32_e32 vcc, 0xffffff9f, v181
	v_cndmask_b32_e32 v113, v113, v171, vcc
	v_cmp_gt_i32_e32 vcc, 0xffffff9e, v181
	v_cndmask_b32_e32 v114, v114, v171, vcc
	v_cmp_gt_i32_e32 vcc, 0xffffff9d, v181
	v_cndmask_b32_e32 v115, v115, v171, vcc
	v_cmp_gt_i32_e32 vcc, 16, v181
	v_cndmask_b32_e32 v140, v140, v171, vcc
	v_cmp_gt_i32_e32 vcc, 15, v181
	v_cndmask_b32_e32 v141, v141, v171, vcc
	v_cmp_gt_i32_e32 vcc, 14, v181
	v_cndmask_b32_e32 v142, v142, v171, vcc
	v_cmp_gt_i32_e32 vcc, 13, v181
	v_cndmask_b32_e32 v143, v143, v171, vcc
	s_branch .LBB0_612
; __device__ __forceinline__ void attn_unit(const bf16* proj, unsigned char* ws, LAS unsigned char* lds, int a) {
;     ...
;             if (kb != n) {
;                 const int sgn = (kb < n) ? 1 : -1, dbase = sgn * (4 * fq - qi);
; #pragma unroll
;                 for (int kt = 0; kt < 8; ++kt)
; #pragma unroll
;                     for (int r = 0; r < 4; ++r) { const int dd = dbase + sgn * (16 * kt + r); st[rt][kt][r] += __builtin_bit_cast(float, (unsigned)(dd >> 31) & 0xF149F2CAu); }
;             }
.Lam_b_next:
	v_cmp_lt_i32_e32 vcc, 0, v181
	v_cndmask_b32_e32 v136, v136, v171, vcc
	v_cmp_lt_i32_e32 vcc, -1, v181
	v_cndmask_b32_e32 v137, v137, v171, vcc
	v_cmp_lt_i32_e32 vcc, -2, v181
	v_cndmask_b32_e32 v138, v138, v171, vcc
	v_cmp_lt_i32_e32 vcc, -3, v181
	v_cndmask_b32_e32 v139, v139, v171, vcc
	v_cmp_lt_i32_e32 vcc, -16, v181
	v_cndmask_b32_e32 v132, v132, v171, vcc
	v_cmp_lt_i32_e32 vcc, 0xffffffef, v181
	v_cndmask_b32_e32 v133, v133, v171, vcc
	v_cmp_lt_i32_e32 vcc, 0xffffffee, v181
	v_cndmask_b32_e32 v134, v134, v171, vcc
	v_cmp_lt_i32_e32 vcc, 0xffffffed, v181
	v_cndmask_b32_e32 v135, v135, v171, vcc
	v_cmp_lt_i32_e32 vcc, 0xffffffe0, v181
	v_cndmask_b32_e32 v128, v128, v171, vcc
	v_cmp_lt_i32_e32 vcc, 0xffffffdf, v181
	v_cndmask_b32_e32 v129, v129, v171, vcc
	v_cmp_lt_i32_e32 vcc, 0xffffffde, v181
	v_cndmask_b32_e32 v130, v130, v171, vcc
	v_cmp_lt_i32_e32 vcc, 0xffffffdd, v181
	v_cndmask_b32_e32 v131, v131, v171, vcc
	v_cmp_lt_i32_e32 vcc, 0xffffffd0, v181
	v_cndmask_b32_e32 v124, v124, v171, vcc
	v_cmp_lt_i32_e32 vcc, 0xffffffcf, v181
	v_cndmask_b32_e32 v125, v125, v171, vcc
	v_cmp_lt_i32_e32 vcc, 0xffffffce, v181
	v_cndmask_b32_e32 v126, v126, v171, vcc
	v_cmp_lt_i32_e32 vcc, 0xffffffcd, v181
	v_cndmask_b32_e32 v127, v127, v171, vcc
	v_cmp_lt_i32_e32 vcc, 0xffffffc0, v181
	v_cndmask_b32_e32 v120, v120, v171, vcc
	v_cmp_lt_i32_e32 vcc, 0xffffffbf, v181
	v_cndmask_b32_e32 v121, v121, v171, vcc
	v_cmp_lt_i32_e32 vcc, 0xffffffbe, v181
	v_cndmask_b32_e32 v122, v122, v171, vcc
	v_cmp_lt_i32_e32 vcc, 0xffffffbd, v181
	v_cndmask_b32_e32 v123, v123, v171, vcc
	v_cmp_lt_i32_e32 vcc, 0xffffffb0, v181
	v_cndmask_b32_e32 v116, v116, v171, vcc
	v_cmp_lt_i32_e32 vcc, 0xffffffaf, v181
	v_cndmask_b32_e32 v117, v117, v171, vcc
	v_cmp_lt_i32_e32 vcc, 0xffffffae, v181
	v_cndmask_b32_e32 v118, v118, v171, vcc
	v_cmp_lt_i32_e32 vcc, 0xffffffad, v181
	v_cndmask_b32_e32 v119, v119, v171, vcc
	v_cmp_lt_i32_e32 vcc, 0xffffffa0, v181
	v_cndmask_b32_e32 v112, v112, v171, vcc
	v_cmp_lt_i32_e32 vcc, 0xffffff9f, v181
	v_cndmask_b32_e32 v113, v113, v171, vcc
	v_cmp_lt_i32_e32 vcc, 0xffffff9e, v181
	v_cndmask_b32_e32 v114, v114, v171, vcc
	v_cmp_lt_i32_e32 vcc, 0xffffff9d, v181
	v_cndmask_b32_e32 v115, v115, v171, vcc
	v_cmp_lt_i32_e32 vcc, 16, v181
	v_cndmask_b32_e32 v140, v140, v171, vcc
	v_cmp_lt_i32_e32 vcc, 15, v181
	v_cndmask_b32_e32 v141, v141, v171, vcc
	v_cmp_lt_i32_e32 vcc, 14, v181
	v_cndmask_b32_e32 v142, v142, v171, vcc
	v_cmp_lt_i32_e32 vcc, 13, v181
	v_cndmask_b32_e32 v143, v143, v171, vcc
